# retention: coalesced q/k/v staging loads (row-major runs) + remapped LDS staging writes
# speedup vs baseline: 1.0301x; 1.0301x over previous
; __device__ __forceinline__ void ret_unit(LAS unsigned char* lds, bf16_t* QKV, float* gn, int b, int h, int vs, bool commit, const float* s00p, const float* ss3, bool skel = false) {
;     ...
;     const int si = w & 3, ti0 = 2 * (w >> 2);
;     u32x4 pq[4], pkv[4], pv[2];
;     const int ls = tid & 63, lc8 = tid >> 6;
.LBB0_1130:
	v_readlane_b32 s52, v254, 6
	s_cmp_lt_i32 s52, 10
	s_cselect_b64 s[6:7], -1, 0
	s_add_u32 s0, s50, 0x180000
	s_addc_u32 s1, s51, 0
	s_and_b64 s[34:35], s[6:7], s[4:5]
	s_xor_b64 s[4:5], s[34:35], -1
	s_cmpk_gt_i32 s2, 0xff
	s_cselect_b64 s[6:7], -1, 0
	s_or_b64 s[4:5], s[4:5], s[6:7]
	v_readlane_b32 s53, v254, 7
	v_readlane_b32 s54, v254, 8
	v_readlane_b32 s55, v254, 9
	s_and_b64 vcc, exec, s[4:5]
	s_cbranch_vccnz .LBB0_1160
	v_and_b32_e32 v128, 63, v176
	s_add_u32 s33, s50, 0x60000
	v_mul_u32_u24_e32 v2, 0x108, v128
	s_addc_u32 s70, s51, 0
	v_bfe_u32 v3, v176, 6, 2
	s_add_i32 s38, 0, 0x10800
	v_lshlrev_b32_e32 v4, 1, v2
	v_lshlrev_b32_e32 v2, 4, v224
	v_and_b32_e32 v130, 15, v176
	v_add3_u32 v129, s38, v4, v2
	v_add3_u32 v131, 0, v4, v2
	v_mul_u32_u24_e32 v4, 0x110, v128
	s_add_i32 s8, 0, 0x18c00
	v_lshlrev_b32_e32 v6, 4, v3
	s_waitcnt lgkmcnt(0)
	v_bfe_u32 v1, v176, 4, 2
	v_add3_u32 v135, s8, v4, v2
	v_or_b32_e32 v4, v6, v130
	s_waitcnt vmcnt(0)
	v_lshlrev_b32_e32 v10, 5, v224
	v_and_b32_e32 v12, 1, v176
	v_mul_u32_u24_e32 v163, 0x210, v4
	v_lshlrev_b32_e32 v4, 2, v1
	v_add_u32_e32 v11, s8, v10
	v_lshlrev_b32_e32 v132, 2, v12
	v_lshrrev_b32_e32 v12, 3, v176
	s_movk_i32 s8, 0x60
	v_lshlrev_b32_e32 v5, 2, v176
	s_add_i32 s71, 0, 0x23800
	v_lshlrev_b32_e32 v164, 3, v1
	v_and_b32_e32 v7, 48, v176
	v_or_b32_e32 v1, v6, v4
	v_and_or_b32 v12, v12, s8, v130
	v_add_u32_e32 v162, s71, v5
	s_movk_i32 s42, 0x210
	v_add_u32_e32 v8, s38, v7
	s_add_i32 s9, 0, 0x21400
	v_lshlrev_b32_e32 v6, 5, v3
	v_and_b32_e32 v5, 12, v5
	v_or_b32_e32 v14, 16, v12
	v_or_b32_e32 v15, 2, v1
	v_or_b32_e32 v16, 3, v1
	v_add3_u32 v6, s9, v6, v164
	v_lshlrev_b32_e32 v165, 1, v5
	v_add_u32_e32 v5, s9, v7
	v_mul_u32_u24_e32 v13, 0x210, v12
	v_mad_u32_u24 v167, v12, s42, v8
	v_cmp_lt_u32_e64 s[8:9], v12, v1
	v_cmp_gt_u32_e64 s[10:11], v12, v1
	v_cmp_lt_u32_e64 s[12:13], v12, v15
	v_cmp_lt_u32_e64 s[14:15], v12, v16
	v_or_b32_e32 v169, v12, v3
	v_mul_u32_u24_e32 v3, 0x90, v12
	v_cmp_lt_u32_e64 s[16:17], v14, v1
	v_cmp_gt_u32_e64 s[18:19], v14, v1
	v_cmp_lt_u32_e64 s[20:21], v14, v15
	v_cmp_lt_u32_e64 s[22:23], v14, v16
	v_mov_b32_e32 v12, 0x2100
	v_mov_b32_e32 v14, 0x4200
	v_mov_b32_e32 v15, 0x6300
	v_mul_u32_u24_e32 v1, 0x210, v130
	v_mad_u32_u24 v12, v130, s42, v12
	v_mad_u32_u24 v14, v130, s42, v14
	v_mad_u32_u24 v15, v130, s42, v15
	v_add3_u32 v170, s38, v1, v164
	v_add3_u32 v171, s38, v12, v164
	v_add3_u32 v172, s38, v14, v164
	v_add3_u32 v173, s38, v15, v164
	s_add_i32 s38, 0, 0x10880
	v_add3_u32 v174, s38, v1, v164
	v_add3_u32 v175, s38, v12, v164
	v_add3_u32 v177, s38, v14, v164
	v_add3_u32 v178, s38, v15, v164
	s_add_i32 s38, 0, 0x108c0
	v_add3_u32 v179, s38, v1, v164
	v_add3_u32 v180, s38, v12, v164
	v_add3_u32 v181, s38, v14, v164
	v_add3_u32 v182, s38, v15, v164
	s_add_i32 s38, 0, 0x10900
	v_add3_u32 v183, s38, v1, v164
	v_add3_u32 v184, s38, v12, v164
	v_add3_u32 v185, s38, v14, v164
	v_add3_u32 v186, s38, v15, v164
	s_add_i32 s38, 0, 0x10940
	v_bfe_u32 v9, v176, 2, 2
	v_add3_u32 v187, s38, v1, v164
	v_add3_u32 v188, s38, v12, v164
	v_add3_u32 v189, s38, v14, v164
	v_add3_u32 v190, s38, v15, v164
	s_add_i32 s38, 0, 0x10980
	v_lshlrev_b32_e32 v0, 3, v224
	v_or_b32_e32 v9, v164, v9
	v_lshrrev_b32_e32 v134, 1, v176
	v_add3_u32 v191, s38, v1, v164
	v_add3_u32 v192, s38, v12, v164
	v_add3_u32 v193, s38, v14, v164
	v_add3_u32 v194, s38, v15, v164
	s_add_i32 s38, 0, 0x109c0
	v_add3_u32 v201, 0, v163, v7
	v_lshlrev_b32_e32 v7, 13, v130
	v_mov_b32_e32 v133, 0
	s_movk_i32 s4, 0x80
	v_add3_u32 v195, s38, v1, v164
	v_add3_u32 v196, s38, v12, v164
	v_add3_u32 v197, s38, v14, v164
	v_add3_u32 v198, s38, v15, v164
	v_mul_u32_u24_e32 v1, 0x90, v130
	v_mul_u32_u24_e32 v12, 0x110, v9
	v_lshl_or_b32 v138, v128, 13, v2
	v_or3_b32 v142, v7, v10, v164
	v_lshlrev_b32_e32 v7, 5, v134
	s_mov_b32 s38, 0x180000
	v_lshlrev_b32_e32 v146, 1, v0
	v_mbcnt_lo_u32_b32 v0, -1, 0
	s_mov_b32 s39, 0
	v_cmp_gt_u32_e64 s[4:5], s4, v176
	v_cmp_gt_u32_e64 s[6:7], 16, v128
	v_lshlrev_b32_e32 v166, 3, v130
	v_lshl_add_u64 v[136:137], s[0:1], 0, v[132:133]
	v_add_u32_e32 v168, 0x2100, v167
	v_mul_u32_u24_e32 v199, 0x210, v9
	v_add3_u32 v200, v11, v165, v12
	v_mov_b32_e32 v139, v133
	v_or_b32_e32 v140, 0xe300800, v138
	v_mov_b32_e32 v141, v133
	v_mov_b32_e32 v143, v133
	s_lshl_b32 s73, s2, 4
	s_lshl_b32 s74, s54, 4
	v_or3_b32 v144, v7, v132, s38
	v_mov_b32_e32 v145, v133
	s_mov_b64 s[42:43], 0x41000
	s_movk_i32 s75, 0x1000
	s_mov_b64 s[52:53], 0x80000
	s_mov_b32 s76, 0x80000
	s_mov_b64 s[54:55], 0x81000
	v_mbcnt_hi_u32_b32 v202, -1, v0
	s_mov_b64 s[56:57], 0x800
	v_lshlrev_b32_e32 v132, 1, v2
	v_lshlrev_b32_e32 v148, 1, v4
	v_add_u32_e32 v203, v8, v13
	v_add_u32_e32 v204, v6, v3
	v_add_u32_e32 v205, v5, v1
	s_mov_b32 s77, s2
	s_mov_b32 s78, s2
	v_lshrrev_b32_e32 v129, 5, v176
	v_mul_u32_u24_e32 v129, 0x210, v129
	v_and_b32_e32 v255, 31, v176
	v_lshl_add_u32 v129, v255, 4, v129
	v_mov_b32_e32 v131, v129
	v_add_u32_e32 v129, 0x10800, v129
	v_lshrrev_b32_e32 v135, 4, v176
	v_mul_u32_u24_e32 v135, 0x110, v135
	v_lshl_add_u32 v135, v130, 4, v135
	v_add_u32_e32 v135, 0x18c00, v135
	v_lshrrev_b32_e32 v146, 5, v176
	v_lshlrev_b32_e32 v255, 4, v255
	v_lshl_or_b32 v146, v146, 13, v255
	v_or_b32_e32 v140, 0xe300800, v146
	v_lshrrev_b32_e32 v138, 4, v176
	v_lshlrev_b32_e32 v255, 4, v130
	v_lshl_or_b32 v138, v138, 13, v255
	s_mov_b64 s[98:99], 0x20000
	s_mov_b64 s[100:101], 0x40000
	s_branch .LBB0_1133

; __device__ __forceinline__ float rms_r(float ss) { return __builtin_amdgcn_rsqf(ss * (1.0f / DM) + RMS_EPS); }
; #define LDS_BAR() do { asm volatile("s_waitcnt lgkmcnt(0)" ::: "memory"); __builtin_amdgcn_s_barrier(); asm volatile("" ::: "memory"); } while (0)
; #define RET_STAGE(Kd, Vd) do { _Pragma("unroll") for (int uu = 0; uu < 4; ++uu) { const int c8 = lc8 + 8 * uu; *(LAS u32x4*)(Ql + ls * 264 + 8 * c8) = pq[uu]; *(LAS u32x4*)((Kd) + ls * 264 + 8 * c8) = pkv[uu]; } \
;         _Pragma("unroll") for (int uu = 0; uu < 2; ++uu) { const int c8 = lc8 + 8 * uu; *(LAS u32x4*)((Vd) + ls * 136 + 8 * c8) = pv[uu]; } } while (0)
; __device__ __forceinline__ void ret_unit(LAS unsigned char* lds, bf16_t* QKV, float* gn, int b, int h, int vs, bool commit, const float* s00p, const float* ss3, bool skel = false) {
;     ...
;     const float l2g = __builtin_amdgcn_logf(1.0f - __builtin_amdgcn_exp2f(-5.0f - (float)h));
;     const float cd = __builtin_amdgcn_exp2f(64.f * l2g);
;     f32x4 state[16];
; #pragma unroll
;     for (int m = 0; m < 16; ++m) state[m] = (f32x4){0.f, 0.f, 0.f, 0.f};
;     const float s00 = s00p[b * 4 + h] * rms_r(ss3[(size_t)b * SEQ]) * rms_r(ss3[(size_t)b * SEQ]) * 0.0625f;
;     const int si = w & 3, ti0 = 2 * (w >> 2);
;     u32x4 pq[4], pkv[4], pv[2];
;     const int ls = tid & 63, lc8 = tid >> 6;
;     ...
;     RET_LOAD(0);
;     LDS_BAR();
;     RET_STAGE(Kb, Vb);
;     RET_LOAD(1);
;     if (tid < 128) st[tid] = 0.f;
;     LDS_BAR();
.LBB0_1133:
	s_ashr_i32 s58, s78, 2
	s_and_b32 s38, s78, 4
	s_and_b32 s58, s58, -8
	s_or_b32 s38, s58, s38
	s_and_b32 s79, s78, 3
	s_or_b32 s58, s38, s79
	s_ashr_i32 s59, s58, 31
	s_ashr_i32 s64, s38, 2
	s_lshl_b64 s[58:59], s[58:59], 2
	s_add_u32 s62, s3, s58
	s_addc_u32 s63, s72, s59
	s_ashr_i32 s65, s64, 31
	s_lshl_b64 s[58:59], s[64:65], 11
	s_lshl_b64 s[68:69], s[64:65], 13
	s_add_u32 s68, s33, s68
	v_mov_b32_e32 v3, s59
	v_mov_b32_e32 v2, s58
	s_addc_u32 s69, s70, s69
	global_load_dword v0, v133, s[62:63]
	global_load_dword v1, v133, s[68:69]
	v_lshlrev_b64 v[2:3], 13, v[2:3]
	s_lshl_b32 s62, s78, 4
	v_lshl_add_u64 v[34:35], s[26:27], 0, v[2:3]
	s_lshl_b32 s38, s79, 9
	s_lshl_b32 s68, s79, 10
	s_mov_b32 s69, s39
	s_and_b32 s62, s62, 0x180
	v_lshl_add_u64 v[2:3], v[34:35], 0, s[38:39]
	s_lshl_b32 s62, s62, 1
	s_mov_b32 s63, s39
	v_lshl_add_u64 v[34:35], v[34:35], 0, s[68:69]
	v_mov_b32_e32 v147, v133
	v_lshl_add_u64 v[34:35], v[34:35], 0, s[62:63]
	v_lshl_add_u64 v[44:45], v[34:35], 0, v[138:139]
	v_add_co_u32_e32 v34, vcc, s75, v44
	v_lshl_add_u64 v[42:43], v[2:3], 0, v[146:147]
	v_lshl_add_u64 v[38:39], v[44:45], 0, s[42:43]
	v_addc_co_u32_e32 v35, vcc, 0, v45, vcc
	s_waitcnt lgkmcnt(0)
	v_lshl_add_u64 v[14:15], v[42:43], 0, s[98:99]
	v_lshl_add_u64 v[26:27], v[14:15], 0, s[98:99]
	v_lshl_add_u64 v[30:31], v[26:27], 0, s[98:99]
	global_load_dwordx4 v[2:5], v[42:43], off
	global_load_dwordx4 v[6:9], v[14:15], off
	global_load_dwordx4 v[10:13], v[42:43], off offset:2048
	global_load_dwordx4 v[14:17], v[14:15], off offset:2048
	global_load_dwordx4 v[18:21], v[26:27], off
	global_load_dwordx4 v[22:25], v[30:31], off
	global_load_dwordx4 v[26:29], v[26:27], off offset:2048
	global_load_dwordx4 v[30:33], v[30:31], off offset:2048
	global_load_dwordx4 v[34:37], v[34:35], off
	global_load_dwordx4 v[38:41], v[38:39], off
	s_waitcnt lgkmcnt(0)
	s_barrier
	v_lshl_add_u64 v[80:81], v[42:43], 0, s[52:53]
	v_lshl_add_u64 v[76:77], v[80:81], 0, s[98:99]
	v_lshl_add_u64 v[84:85], v[76:77], 0, s[98:99]
	v_lshl_add_u64 v[92:93], v[84:85], 0, s[98:99]
	global_load_dwordx4 v[64:67], v[76:77], off
	global_load_dwordx4 v[68:71], v[84:85], off
	global_load_dwordx4 v[72:75], v[80:81], off
	global_load_dwordx4 v[88:91], v[92:93], off
	global_load_dwordx4 v[76:79], v[76:77], off offset:2048
	global_load_dwordx4 v[84:87], v[84:85], off offset:2048
	global_load_dwordx4 v[80:83], v[80:81], off offset:2048
	global_load_dwordx4 v[92:95], v[92:93], off offset:2048
	v_lshl_add_u64 v[98:99], v[44:45], 0, s[54:55]
	v_lshl_add_u64 v[100:101], v[98:99], 0, s[100:101]
	global_load_dwordx4 v[96:99], v[98:99], off
	global_load_dwordx4 v[100:103], v[100:101], off
	s_waitcnt vmcnt(19)
	ds_write_b128 v129, v[2:5]
	s_waitcnt vmcnt(17)
	ds_write_b128 v131, v[10:13]
	ds_write_b128 v129, v[6:9] offset:8448
	s_waitcnt vmcnt(16)
	ds_write_b128 v131, v[14:17] offset:8448
	s_waitcnt vmcnt(15)
	ds_write_b128 v129, v[18:21] offset:16896
	s_waitcnt vmcnt(13)
	ds_write_b128 v131, v[26:29] offset:16896
	ds_write_b128 v129, v[22:25] offset:25344
	s_waitcnt vmcnt(12)
	ds_write_b128 v131, v[30:33] offset:25344
	s_waitcnt vmcnt(11)
	ds_write_b128 v135, v[34:37]
	s_waitcnt vmcnt(10)
	ds_write_b128 v135, v[38:41] offset:8704
	s_and_saveexec_b64 s[68:69], s[4:5]
	ds_write_b32 v162, v133
	s_or_b64 exec, exec, s[68:69]
	v_cvt_f32_ubyte0_e32 v2, s79
	v_sub_f32_e32 v2, 0xc0a00000, v2
	v_exp_f32_e32 v2, v2
	v_mov_b32_e32 v3, 0x358637bd
	v_fmamk_f32 v1, v1, 0x3a800000, v3
	v_rsq_f32_e32 v1, v1
	v_sub_f32_e32 v2, 1.0, v2
	v_log_f32_e32 v2, v2
	s_and_b32 s63, s77, 3
	s_lshl_b32 s68, s73, 1
	s_lshl_b32 s80, s63, 9
	v_mul_f32_e32 v2, 0x42800000, v2
	s_and_b32 s83, s68, 0x300
	v_exp_f32_e32 v150, v2
	s_lshl_b64 s[68:69], s[64:65], 24
	s_lshl_b32 s82, s63, 10
	s_or_b32 s80, s68, s80
	s_mov_b32 s81, s69
	s_lshl_b32 s63, s63, 3
	v_mul_f32_e32 v0, v0, v1
	s_waitcnt lgkmcnt(0)
	s_barrier
	v_lshl_add_u64 v[154:155], s[80:81], 0, v[140:141]
	s_or_b32 s80, s83, s82
	s_lshl_b64 s[64:65], s[64:65], 16
	v_mul_f32_e32 v0, v1, v0
	s_or_b32 s68, s68, s80
	s_or_b32 s64, s64, s63
	v_mov_b32_e32 v40, 0
	v_mul_f32_e32 v147, 0x3d800000, v0
	v_mov_b32_e32 v152, v150
	v_mov_b32_e32 v153, v150
	v_lshl_add_u64 v[156:157], s[68:69], 0, v[142:143]
	v_lshl_add_u64 v[158:159], s[64:65], 0, v[144:145]
	v_lshl_add_u64 v[160:161], s[68:69], 0, v[138:139]
	s_mov_b32 s63, 0
	v_mov_b32_e32 v41, v40
	v_mov_b32_e32 v42, v40
	v_mov_b32_e32 v43, v40
	v_mov_b32_e32 v44, v40
	v_mov_b32_e32 v45, v40
	v_mov_b32_e32 v46, v40
	v_mov_b32_e32 v47, v40
	v_mov_b32_e32 v48, v40
	v_mov_b32_e32 v49, v40
	v_mov_b32_e32 v50, v40
	v_mov_b32_e32 v51, v40
	v_mov_b32_e32 v52, v40
	v_mov_b32_e32 v53, v40
	v_mov_b32_e32 v54, v40
	v_mov_b32_e32 v55, v40
	v_mov_b32_e32 v56, v40
	v_mov_b32_e32 v57, v40
	v_mov_b32_e32 v58, v40
	v_mov_b32_e32 v59, v40
	v_mov_b32_e32 v60, v40
	v_mov_b32_e32 v61, v40
	v_mov_b32_e32 v62, v40
	v_mov_b32_e32 v63, v40
	v_mov_b32_e32 v36, v40
	v_mov_b32_e32 v37, v40
	v_mov_b32_e32 v38, v40
	v_mov_b32_e32 v39, v40
	v_mov_b32_e32 v32, v40
	v_mov_b32_e32 v33, v40
	v_mov_b32_e32 v34, v40
	v_mov_b32_e32 v35, v40
	v_mov_b32_e32 v28, v40
	v_mov_b32_e32 v29, v40
	v_mov_b32_e32 v30, v40
	v_mov_b32_e32 v31, v40
	v_mov_b32_e32 v24, v40
	v_mov_b32_e32 v25, v40
	v_mov_b32_e32 v26, v40
	v_mov_b32_e32 v27, v40
	v_mov_b32_e32 v20, v40
	v_mov_b32_e32 v21, v40
	v_mov_b32_e32 v22, v40
	v_mov_b32_e32 v23, v40
	v_mov_b32_e32 v16, v40
	v_mov_b32_e32 v17, v40
	v_mov_b32_e32 v18, v40
	v_mov_b32_e32 v19, v40
	v_mov_b32_e32 v12, v40
	v_mov_b32_e32 v13, v40
	v_mov_b32_e32 v14, v40
	v_mov_b32_e32 v15, v40
	v_mov_b32_e32 v8, v40
	v_mov_b32_e32 v9, v40
	v_mov_b32_e32 v10, v40
	v_mov_b32_e32 v11, v40
	v_mov_b32_e32 v4, v40
	v_mov_b32_e32 v5, v40
	v_mov_b32_e32 v6, v40
	v_mov_b32_e32 v7, v40
	v_mov_b32_e32 v0, v40
	v_mov_b32_e32 v1, v40
	v_mov_b32_e32 v2, v40
	v_mov_b32_e32 v3, v40
	s_waitcnt vmcnt(0)
	s_branch .LBB0_1137

; #define LAS __attribute__((address_space(3)))
; __device__ __forceinline__ u32x2 pack4(f32x4 v) { return (u32x2){pk2(v[0], v[1]), pk2(v[2], v[3])}; }
; #define SB0 __builtin_amdgcn_sched_barrier(0)
; #define SB0 __builtin_amdgcn_sched_barrier(0)
; #define RA_LOAD(ks_) do { ka[(ks_) % 3] = *(const LAS bf16x8*)(Kl + (16 * si + fr) * 264 + 32 * (ks_) + 8 * fq); \
;               _Pragma("unroll") for (int tt = 0; tt < 2; ++tt) qb[(ks_) % 3][tt] = *(const LAS bf16x8*)(Ql + (16 * (ti0 + tt) + fr) * 264 + 32 * (ks_) + 8 * fq); } while (0)
; __device__ __forceinline__ void ret_unit(LAS unsigned char* lds, bf16_t* QKV, float* gn, int b, int h, int vs, bool commit, const float* s00p, const float* ss3, bool skel = false) {
;     ...
;         if (!skel) {
;         { f32x4 sv[2] = {(f32x4){0.f, 0.f, 0.f, 0.f}, (f32x4){0.f, 0.f, 0.f, 0.f}};
;           bf16x8 ka[3], qb[3][2];
;     ...
;           RA_LOAD(0); RA_LOAD(1); SB0;
; #pragma unroll
;           for (int ks = 0; ks < 8; ++ks) { if (ks + 2 < 8) RA_LOAD(ks + 2); SB0;
; #pragma unroll
;               for (int tt = 0; tt < 2; ++tt) sv[tt] = __builtin_amdgcn_mfma_f32_16x16x32_bf16(ka[ks % 3], qb[ks % 3][tt], sv[tt], 0, 0, 0);
;               SB0; }
;     ...
; #pragma unroll
;           for (int tt = 0; tt < 2; ++tt) { const int t = 16 * (ti0 + tt) + fr; f32x4 pvv;
; #pragma unroll
;               for (int r = 0; r < 4; ++r) { const int sidx = 16 * si + 4 * fq + r; pvv[r] = t >= sidx ? sv[tt][r] : 0.f; }
;               if (c == 0 && t == 0 && si == 0 && fq == 0) pvv[0] = s00;
;               *(LAS u32x2*)(Pl + t * 72 + 16 * si + 4 * fq) = pack4(pvv); } }
;         { u32x4 qf[3][4];
;     ...
;           RC_LOAD(0); RC_LOAD(1); SB0;
; #pragma unroll
;           for (int kk = 0; kk < 8; ++kk) { if (kk + 2 < 8) RC_LOAD(kk + 2);
;               const u32x2 s0 = pack4(state[2 * kk]), s1 = pack4(state[2 * kk + 1]);
;               const u32x4 aw = (u32x4){s0.x, s0.y, s1.x, s1.y}; const bf16x8 afrag = __builtin_bit_cast(bf16x8, aw);
;               SB0;
; #pragma unroll
;               for (int n = 0; n < 4; ++n) oacc[n] = __builtin_amdgcn_mfma_f32_16x16x32_bf16(afrag, __builtin_bit_cast(bf16x8, qf[kk % 3][n]), oacc[n], 0, 0, 0);
;               SB0; }
.LBB0_1137:
	s_and_b32 s65, s63, 1
	s_mul_i32 s64, s65, 0x8400
	s_add_i32 s64, s64, 0
	v_lshlrev_b32_e32 v104, 1, v164
	v_add3_u32 v149, s64, v163, v104
	ds_read_b128 v[104:107], v203
	s_waitcnt lgkmcnt(1)
	ds_read_b128 v[108:111], v203 offset:8448
	ds_read_b128 v[112:115], v149
	ds_read_b128 v[116:119], v149 offset:64
	ds_read_b128 v[120:123], v167 offset:64
	ds_read_b128 v[124:127], v168 offset:64
	ds_read_b128 v[206:209], v149 offset:128
	ds_read_b128 v[210:213], v203 offset:128
	ds_read_b128 v[214:217], v203 offset:8576
	s_waitcnt lgkmcnt(6)
	v_mfma_f32_16x16x32_bf16 v[104:107], v[112:115], v[104:107], 0
	v_mfma_f32_16x16x32_bf16 v[108:111], v[112:115], v[108:111], 0
	ds_read_b128 v[112:115], v149 offset:192
	ds_read_b128 v[218:221], v203 offset:192
	ds_read_b128 v[222:225], v203 offset:8640
	s_waitcnt lgkmcnt(7)
	v_mfma_f32_16x16x32_bf16 v[104:107], v[116:119], v[120:123], v[104:107]
	s_waitcnt lgkmcnt(6)
	v_mfma_f32_16x16x32_bf16 v[108:111], v[116:119], v[124:127], v[108:111]
	ds_read_b128 v[116:119], v149 offset:256
	ds_read_b128 v[120:123], v203 offset:256
	ds_read_b128 v[124:127], v203 offset:8704
	s_waitcnt lgkmcnt(7)
	v_mfma_f32_16x16x32_bf16 v[104:107], v[206:209], v[210:213], v[104:107]
	s_waitcnt lgkmcnt(6)
	v_mfma_f32_16x16x32_bf16 v[108:111], v[206:209], v[214:217], v[108:111]
	ds_read_b128 v[206:209], v149 offset:320
	ds_read_b128 v[210:213], v203 offset:320
	ds_read_b128 v[214:217], v203 offset:8768
	s_waitcnt lgkmcnt(7)
	v_mfma_f32_16x16x32_bf16 v[104:107], v[112:115], v[218:221], v[104:107]
	s_waitcnt lgkmcnt(6)
	v_mfma_f32_16x16x32_bf16 v[108:111], v[112:115], v[222:225], v[108:111]
	ds_read_b128 v[112:115], v149 offset:384
	ds_read_b128 v[218:221], v203 offset:384
	ds_read_b128 v[222:225], v203 offset:8832
	s_waitcnt lgkmcnt(7)
	v_mfma_f32_16x16x32_bf16 v[104:107], v[116:119], v[120:123], v[104:107]
	s_waitcnt lgkmcnt(6)
	v_mfma_f32_16x16x32_bf16 v[108:111], v[116:119], v[124:127], v[108:111]
	ds_read_b128 v[116:119], v149 offset:448
	ds_read_b128 v[120:123], v203 offset:448
	ds_read_b128 v[124:127], v203 offset:8896
	s_waitcnt lgkmcnt(7)
	v_mfma_f32_16x16x32_bf16 v[104:107], v[206:209], v[210:213], v[104:107]
	s_waitcnt lgkmcnt(6)
	v_mfma_f32_16x16x32_bf16 v[108:111], v[206:209], v[214:217], v[108:111]
	s_waitcnt lgkmcnt(4)
	v_mfma_f32_16x16x32_bf16 v[104:107], v[112:115], v[218:221], v[104:107]
	s_waitcnt lgkmcnt(3)
	v_mfma_f32_16x16x32_bf16 v[108:111], v[112:115], v[222:225], v[108:111]
	s_waitcnt lgkmcnt(1)
	v_mfma_f32_16x16x32_bf16 v[104:107], v[116:119], v[120:123], v[104:107]
	s_waitcnt lgkmcnt(0)
	v_mfma_f32_16x16x32_bf16 v[108:111], v[116:119], v[124:127], v[108:111]
	v_or_b32_e32 v112, s63, v169
	v_cmp_eq_u32_e32 vcc, 0, v112
	s_nop 3
	v_cndmask_b32_e64 v104, v104, 0, s[8:9]
	s_and_b64 vcc, vcc, s[6:7]
	v_cndmask_b32_e64 v105, 0, v105, s[10:11]
	v_cndmask_b32_e32 v104, v104, v147, vcc
	v_cndmask_b32_e64 v106, v106, 0, s[12:13]
	v_cndmask_b32_e64 v107, v107, 0, s[14:15]
	v_cvt_pk_bf16_f32 v104, v104, v105
	v_cvt_pk_bf16_f32 v105, v106, v107
	ds_write_b64 v204, v[104:105]
	v_cndmask_b32_e64 v104, v108, 0, s[16:17]
	v_cndmask_b32_e64 v105, 0, v109, s[18:19]
	v_cndmask_b32_e64 v106, v110, 0, s[20:21]
	v_cndmask_b32_e64 v107, v111, 0, s[22:23]
	v_cvt_pk_bf16_f32 v104, v104, v105
	v_cvt_pk_bf16_f32 v105, v106, v107
	ds_write_b64 v204, v[104:105] offset:2304
	ds_read2_b64 v[104:107], v170 offset1:4
	ds_read2_b64 v[108:111], v171 offset1:4
	ds_read2_b64 v[112:115], v172 offset1:4
	ds_read2_b64 v[116:119], v173 offset1:4
	ds_read2_b64 v[120:123], v170 offset0:8 offset1:12
	ds_read2_b64 v[124:127], v171 offset0:8 offset1:12
	ds_read2_b64 v[206:209], v172 offset0:8 offset1:12
	ds_read2_b64 v[210:213], v173 offset0:8 offset1:12
	ds_read2_b64 v[214:217], v174 offset1:4
	ds_read2_b64 v[218:221], v175 offset1:4
	ds_read2_b64 v[222:225], v177 offset1:4
	ds_read2_b64 v[226:229], v178 offset1:4
	v_cvt_pk_bf16_f32 v230, v60, v61
	v_cvt_pk_bf16_f32 v231, v62, v63
	v_cvt_pk_bf16_f32 v232, v56, v57
	v_cvt_pk_bf16_f32 v233, v58, v59
	s_waitcnt lgkmcnt(11)
	v_mfma_f32_16x16x32_bf16 v[104:107], v[230:233], v[104:107], 0
	s_waitcnt lgkmcnt(10)
	v_mfma_f32_16x16x32_bf16 v[108:111], v[230:233], v[108:111], 0
	s_waitcnt lgkmcnt(9)
	v_mfma_f32_16x16x32_bf16 v[112:115], v[230:233], v[112:115], 0
	s_waitcnt lgkmcnt(8)
	v_mfma_f32_16x16x32_bf16 v[116:119], v[230:233], v[116:119], 0
	ds_read2_b64 v[230:233], v179 offset1:4
	ds_read2_b64 v[234:237], v180 offset1:4
	ds_read2_b64 v[238:241], v181 offset1:4
	ds_read2_b64 v[242:245], v182 offset1:4
	v_cvt_pk_bf16_f32 v246, v52, v53
	v_cvt_pk_bf16_f32 v247, v54, v55
	v_cvt_pk_bf16_f32 v248, v48, v49
	v_cvt_pk_bf16_f32 v249, v50, v51
	s_waitcnt lgkmcnt(11)
	v_mfma_f32_16x16x32_bf16 v[104:107], v[246:249], v[120:123], v[104:107]
	s_waitcnt lgkmcnt(10)
	v_mfma_f32_16x16x32_bf16 v[108:111], v[246:249], v[124:127], v[108:111]
	s_waitcnt lgkmcnt(9)
	v_mfma_f32_16x16x32_bf16 v[112:115], v[246:249], v[206:209], v[112:115]
	s_waitcnt lgkmcnt(8)
	v_mfma_f32_16x16x32_bf16 v[116:119], v[246:249], v[210:213], v[116:119]
	ds_read2_b64 v[120:123], v183 offset1:4
	ds_read2_b64 v[124:127], v184 offset1:4
	ds_read2_b64 v[206:209], v185 offset1:4
	ds_read2_b64 v[210:213], v186 offset1:4
	v_cvt_pk_bf16_f32 v246, v44, v45
	v_cvt_pk_bf16_f32 v247, v46, v47
	v_cvt_pk_bf16_f32 v248, v40, v41
	v_cvt_pk_bf16_f32 v249, v42, v43
	s_waitcnt lgkmcnt(11)
; __device__ __forceinline__ u32x2 pack4(f32x4 v) { return (u32x2){pk2(v[0], v[1]), pk2(v[2], v[3])}; }
; #define LDS_BAR() do { asm volatile("s_waitcnt lgkmcnt(0)" ::: "memory"); __builtin_amdgcn_s_barrier(); asm volatile("" ::: "memory"); } while (0)
; #define SB0 __builtin_amdgcn_sched_barrier(0)
; #define RET_STAGE(Kd, Vd) do { _Pragma("unroll") for (int uu = 0; uu < 4; ++uu) { const int c8 = lc8 + 8 * uu; *(LAS u32x4*)(Ql + ls * 264 + 8 * c8) = pq[uu]; *(LAS u32x4*)((Kd) + ls * 264 + 8 * c8) = pkv[uu]; } \
;         _Pragma("unroll") for (int uu = 0; uu < 2; ++uu) { const int c8 = lc8 + 8 * uu; *(LAS u32x4*)((Vd) + ls * 136 + 8 * c8) = pv[uu]; } } while (0)
; #define SB0 __builtin_amdgcn_sched_barrier(0)
; #define RC_LOAD(kk_) do { _Pragma("unroll") for (int n = 0; n < 4; ++n) { const u32x2 lo = *(const LAS u32x2*)(Ql + (16 * n + fr) * 264 + 32 * (kk_) + 4 * fq), hi = *(const LAS u32x2*)(Ql + (16 * n + fr) * 264 + 32 * (kk_) + 16 + 4 * fq); \
;               qf[(kk_) % 3][n] = (u32x4){lo.x, lo.y, hi.x, hi.y}; } } while (0)
; __device__ __forceinline__ void ret_unit(LAS unsigned char* lds, bf16_t* QKV, float* gn, int b, int h, int vs, bool commit, const float* s00p, const float* ss3, bool skel = false) {
;     ...
;           for (int kk = 0; kk < 8; ++kk) { if (kk + 2 < 8) RC_LOAD(kk + 2);
;               const u32x2 s0 = pack4(state[2 * kk]), s1 = pack4(state[2 * kk + 1]);
;               const u32x4 aw = (u32x4){s0.x, s0.y, s1.x, s1.y}; const bf16x8 afrag = __builtin_bit_cast(bf16x8, aw);
;               SB0;
; #pragma unroll
;               for (int n = 0; n < 4; ++n) oacc[n] = __builtin_amdgcn_mfma_f32_16x16x32_bf16(afrag, __builtin_bit_cast(bf16x8, qf[kk % 3][n]), oacc[n], 0, 0, 0);
;               SB0; }
;     ...
;         }
; #pragma unroll
;         for (int n = 0; n < 4; ++n) oacc[n] = oacc[n] * cd;
;         }
;         LDS_BAR();
;         if (c + 1 < 32) { RET_STAGE(Kn, Vn); if (c + 2 < 32) RET_LOAD(c + 2); }
	v_mfma_f32_16x16x32_bf16 v[104:107], v[246:249], v[214:217], v[104:107]
	s_waitcnt lgkmcnt(10)
	v_mfma_f32_16x16x32_bf16 v[108:111], v[246:249], v[218:221], v[108:111]
	s_waitcnt lgkmcnt(9)
	v_mfma_f32_16x16x32_bf16 v[112:115], v[246:249], v[222:225], v[112:115]
	s_waitcnt lgkmcnt(8)
	v_mfma_f32_16x16x32_bf16 v[116:119], v[246:249], v[226:229], v[116:119]
	ds_read2_b64 v[214:217], v187 offset1:4
	ds_read2_b64 v[218:221], v188 offset1:4
	ds_read2_b64 v[222:225], v189 offset1:4
	ds_read2_b64 v[226:229], v190 offset1:4
	v_cvt_pk_bf16_f32 v246, v36, v37
	v_cvt_pk_bf16_f32 v247, v38, v39
	v_cvt_pk_bf16_f32 v248, v32, v33
	v_cvt_pk_bf16_f32 v249, v34, v35
	s_waitcnt lgkmcnt(11)
	v_mfma_f32_16x16x32_bf16 v[104:107], v[246:249], v[230:233], v[104:107]
	s_waitcnt lgkmcnt(10)
	v_mfma_f32_16x16x32_bf16 v[108:111], v[246:249], v[234:237], v[108:111]
	s_waitcnt lgkmcnt(9)
	v_mfma_f32_16x16x32_bf16 v[112:115], v[246:249], v[238:241], v[112:115]
	s_waitcnt lgkmcnt(8)
	v_mfma_f32_16x16x32_bf16 v[116:119], v[246:249], v[242:245], v[116:119]
	ds_read2_b64 v[230:233], v191 offset1:4
	ds_read2_b64 v[234:237], v192 offset1:4
	ds_read2_b64 v[238:241], v193 offset1:4
	ds_read2_b64 v[242:245], v194 offset1:4
	v_cvt_pk_bf16_f32 v246, v28, v29
	v_cvt_pk_bf16_f32 v247, v30, v31
	v_cvt_pk_bf16_f32 v248, v24, v25
	v_cvt_pk_bf16_f32 v249, v26, v27
	s_waitcnt lgkmcnt(11)
	v_mfma_f32_16x16x32_bf16 v[104:107], v[246:249], v[120:123], v[104:107]
	s_waitcnt lgkmcnt(10)
	v_mfma_f32_16x16x32_bf16 v[108:111], v[246:249], v[124:127], v[108:111]
	s_waitcnt lgkmcnt(9)
	v_mfma_f32_16x16x32_bf16 v[112:115], v[246:249], v[206:209], v[112:115]
	s_waitcnt lgkmcnt(8)
	v_mfma_f32_16x16x32_bf16 v[116:119], v[246:249], v[210:213], v[116:119]
	ds_read2_b64 v[120:123], v195 offset1:4
	ds_read2_b64 v[124:127], v196 offset1:4
	ds_read2_b64 v[206:209], v197 offset1:4
	ds_read2_b64 v[210:213], v198 offset1:4
	v_cvt_pk_bf16_f32 v246, v20, v21
	v_cvt_pk_bf16_f32 v247, v22, v23
	v_cvt_pk_bf16_f32 v248, v16, v17
	v_cvt_pk_bf16_f32 v249, v18, v19
	s_waitcnt lgkmcnt(11)
	v_mfma_f32_16x16x32_bf16 v[104:107], v[246:249], v[214:217], v[104:107]
	s_waitcnt lgkmcnt(10)
	v_mfma_f32_16x16x32_bf16 v[108:111], v[246:249], v[218:221], v[108:111]
	s_waitcnt lgkmcnt(9)
	v_mfma_f32_16x16x32_bf16 v[112:115], v[246:249], v[222:225], v[112:115]
	s_waitcnt lgkmcnt(8)
	v_mfma_f32_16x16x32_bf16 v[116:119], v[246:249], v[226:229], v[116:119]
	v_cvt_pk_bf16_f32 v214, v12, v13
	v_cvt_pk_bf16_f32 v215, v14, v15
	v_cvt_pk_bf16_f32 v216, v8, v9
	v_cvt_pk_bf16_f32 v217, v10, v11
	s_waitcnt lgkmcnt(7)
	v_mfma_f32_16x16x32_bf16 v[104:107], v[214:217], v[230:233], v[104:107]
	s_waitcnt lgkmcnt(6)
	v_mfma_f32_16x16x32_bf16 v[108:111], v[214:217], v[234:237], v[108:111]
	s_waitcnt lgkmcnt(5)
	v_mfma_f32_16x16x32_bf16 v[218:221], v[214:217], v[238:241], v[112:115]
	s_waitcnt lgkmcnt(4)
	v_mfma_f32_16x16x32_bf16 v[214:217], v[214:217], v[242:245], v[116:119]
	v_cvt_pk_bf16_f32 v222, v4, v5
	v_cvt_pk_bf16_f32 v223, v6, v7
	v_cvt_pk_bf16_f32 v224, v0, v1
	v_cvt_pk_bf16_f32 v225, v2, v3
	s_waitcnt lgkmcnt(3)
	v_mfma_f32_16x16x32_bf16 v[116:119], v[222:225], v[120:123], v[104:107]
	s_waitcnt lgkmcnt(2)
	v_mfma_f32_16x16x32_bf16 v[112:115], v[222:225], v[124:127], v[108:111]
	s_waitcnt lgkmcnt(1)
	v_mfma_f32_16x16x32_bf16 v[108:111], v[222:225], v[206:209], v[218:221]
	s_waitcnt lgkmcnt(0)
	v_mfma_f32_16x16x32_bf16 v[104:107], v[222:225], v[210:213], v[214:217]
	s_xor_b32 s68, s65, 1
	s_waitcnt lgkmcnt(0)
	s_barrier
	s_mul_i32 s69, s68, 0x8400
	s_mulk_i32 s68, 0x4400
	v_add_u32_e32 v120, s69, v131
	s_waitcnt vmcnt(7)
	ds_write_b128 v129, v[72:75]
	ds_write_b128 v120, v[80:83]
	ds_write_b128 v129, v[64:67] offset:8448
	ds_write_b128 v120, v[76:79] offset:8448
	ds_write_b128 v129, v[68:71] offset:16896
	ds_write_b128 v120, v[84:87] offset:16896
	ds_write_b128 v129, v[88:91] offset:25344
	s_waitcnt vmcnt(6)
	ds_write_b128 v120, v[92:95] offset:25344
	v_add_u32_e32 v120, s68, v135
	s_cmp_gt_u32 s63, 29
	s_waitcnt vmcnt(5)
	ds_write_b128 v120, v[96:99]
	s_waitcnt vmcnt(4)
	ds_write_b128 v120, v[100:103] offset:8704
	s_cbranch_scc1 .LBB0_1139
	v_lshl_add_u64 v[80:81], s[50:51], 0, v[154:155]
	v_lshl_add_u64 v[76:77], v[80:81], 0, s[98:99]
	v_lshl_add_u64 v[84:85], v[76:77], 0, s[98:99]
	v_lshl_add_u64 v[92:93], v[84:85], 0, s[98:99]
	global_load_dwordx4 v[72:75], v[80:81], off offset:-2048
	global_load_dwordx4 v[64:67], v[76:77], off offset:-2048
	global_load_dwordx4 v[80:83], v[80:81], off
	global_load_dwordx4 v[76:79], v[76:77], off
	global_load_dwordx4 v[68:71], v[84:85], off offset:-2048
	global_load_dwordx4 v[88:91], v[92:93], off offset:-2048
	global_load_dwordx4 v[84:87], v[84:85], off
	global_load_dwordx4 v[92:95], v[92:93], off
	v_lshl_add_u64 v[96:97], s[50:51], 0, v[160:161]
	v_add_co_u32_e32 v98, vcc, 0xe301000, v96
	s_nop 1
	v_addc_co_u32_e32 v99, vcc, 0, v97, vcc
	v_lshl_add_u64 v[100:101], v[98:99], 0, s[100:101]
	global_load_dwordx4 v[96:99], v[98:99], off
	global_load_dwordx4 v[100:103], v[100:101], off

; __global__ void __launch_bounds__(NTHR, 2) fwd_megakernel(Args a) {
	.amdhsa_kernel _Z14fwd_megakernel4Args
		.amdhsa_group_segment_fixed_size 0
		.amdhsa_private_segment_fixed_size 0
		.amdhsa_kernarg_size 456
		.amdhsa_user_sgpr_count 2
		.amdhsa_user_sgpr_dispatch_ptr 0
		.amdhsa_user_sgpr_queue_ptr 0
		.amdhsa_user_sgpr_kernarg_segment_ptr 1
		.amdhsa_user_sgpr_dispatch_id 0
		.amdhsa_user_sgpr_kernarg_preload_length 0
		.amdhsa_user_sgpr_kernarg_preload_offset 0
		.amdhsa_user_sgpr_private_segment_size 0
		.amdhsa_uses_dynamic_stack 0
		.amdhsa_enable_private_segment 0
		.amdhsa_system_sgpr_workgroup_id_x 1
		.amdhsa_system_sgpr_workgroup_id_y 0
		.amdhsa_system_sgpr_workgroup_id_z 0
		.amdhsa_system_sgpr_workgroup_info 0
		.amdhsa_system_vgpr_workitem_id 2
		.amdhsa_next_free_vgpr 256
		.amdhsa_next_free_sgpr 102
		.amdhsa_accum_offset 256
		.amdhsa_reserve_vcc 1
		.amdhsa_float_round_mode_32 0
		.amdhsa_float_round_mode_16_64 0
		.amdhsa_float_denorm_mode_32 3
		.amdhsa_float_denorm_mode_16_64 3
		.amdhsa_dx10_clamp 1
		.amdhsa_ieee_mode 1
		.amdhsa_fp16_overflow 0
		.amdhsa_tg_split 0
		.amdhsa_exception_fp_ieee_invalid_op 0
		.amdhsa_exception_fp_denorm_src 0
		.amdhsa_exception_fp_ieee_div_zero 0
		.amdhsa_exception_fp_ieee_overflow 0
		.amdhsa_exception_fp_ieee_underflow 0
		.amdhsa_exception_fp_ieee_inexact 0
		.amdhsa_exception_int_div_zero 0
	.end_amdhsa_kernel

; __global__ void __launch_bounds__(NTHR, 2) fwd_megakernel(Args a) {
amdhsa.kernels:
  - .agpr_count:     0
    .args:
      - .offset:         0
        .size:           200
        .value_kind:     by_value
      - .offset:         200
        .size:           4
        .value_kind:     hidden_block_count_x
      - .offset:         204
        .size:           4
        .value_kind:     hidden_block_count_y
      - .offset:         208
        .size:           4
        .value_kind:     hidden_block_count_z
      - .offset:         212
        .size:           2
        .value_kind:     hidden_group_size_x
      - .offset:         214
        .size:           2
        .value_kind:     hidden_group_size_y
      - .offset:         216
        .size:           2
        .value_kind:     hidden_group_size_z
      - .offset:         218
        .size:           2
        .value_kind:     hidden_remainder_x
      - .offset:         220
        .size:           2
        .value_kind:     hidden_remainder_y
      - .offset:         222
        .size:           2
        .value_kind:     hidden_remainder_z
      - .offset:         240
        .size:           8
        .value_kind:     hidden_global_offset_x
      - .offset:         248
        .size:           8
        .value_kind:     hidden_global_offset_y
      - .offset:         256
        .size:           8
        .value_kind:     hidden_global_offset_z
      - .offset:         264
        .size:           2
        .value_kind:     hidden_grid_dims
      - .offset:         288
        .size:           8
        .value_kind:     hidden_multigrid_sync_arg
      - .offset:         320
        .size:           4
        .value_kind:     hidden_dynamic_lds_size
    .group_segment_fixed_size: 0
    .kernarg_segment_align: 8
    .kernarg_segment_size: 456
    .language:       OpenCL C
    .language_version:
      - 2
      - 0
    .max_flat_workgroup_size: 512
    .name:           _Z14fwd_megakernel4Args
    .private_segment_fixed_size: 0
    .sgpr_count:     108
    .sgpr_spill_count: 74
    .symbol:         _Z14fwd_megakernel4Args.kd
    .uniform_work_group_size: 1
    .uses_dynamic_stack: false
    .vgpr_count:     256
    .vgpr_spill_count: 0
    .wavefront_size: 64
